# PP: non-temporal hint on the z-gate loads (read once) to keep the rewritten P rows resident in L2 for the out-projection
# baseline (speedup 1.0000x reference)
; DI void phase_post(const Params& p, int l, int G, int bid) {
;     ...
;     if (bid * 8 + wave < MSEG * 2) PP_LOAD(bid * 8 + wave);
;     for (int it = bid * 8 + wave; it < MSEG * 2; it += G * 8) {
;         const int lrow = it >> 1, grp = it & 1;
;         bf16_t* cp = P + (size_t)lrow * NPC + grp * 1024 + 16 * lane;
;         const u32x4 c0 = nc0, c1 = nc1, z0 = nz0, z1 = nz1, o0 = no0, o1 = no1;
;         const float inv = (grp == 0) ? 1.0f / ndn : 1.f;
;         if (it + G * 8 < MSEG * 2) PP_LOAD(it + G * 8);
.LBB0_691:
.LBB0_692:
	v_readlane_b32 s0, v252, 4
	v_readlane_b32 s1, v252, 5
	s_cmp_ge_i32 s88, s0
	s_cselect_b64 s[0:1], -1, 0
	s_cmp_lt_i32 s88, s33
	s_cselect_b64 s[8:9], -1, 0
	s_and_b64 s[0:1], s[0:1], s[8:9]
	s_andn2_b64 vcc, exec, s[0:1]
	v_readlane_b32 s0, v250, 58
	s_add_i32 s26, s0, 6
	s_cbranch_vccnz .LBB0_772
	s_waitcnt vmcnt(0)
	v_mov_b32_e32 v2, v202
	v_readlane_b32 s0, v251, 61
	v_readlane_b32 s38, v251, 58
	s_lshl_b32 s0, s0, 9
	s_lshl_b32 s38, s38, 7
	s_add_i32 s0, s0, s38
	s_add_i32 s38, s0, 0x80
	v_ashrrev_i32_e32 v0, 6, v2
	v_readlane_b32 s1, v250, 3
	v_add_u32_e32 v60, s0, v0
	s_mov_b32 s0, 0x8000
	v_cmp_gt_i32_e32 vcc, s0, v60
	s_and_saveexec_b64 s[42:43], vcc
	s_cbranch_execz .LBB0_704
	v_and_b32_e32 v3, 63, v2
	v_ashrrev_i32_e32 v36, 1, v60
	v_mov_b64_e32 v[4:5], s[24:25]
	v_bfe_u32 v35, v2, 6, 1
	s_add_u32 s98, s92, 0x800000
	s_addc_u32 s99, s93, 0
	s_add_u32 s100, s92, 0xa80000
	s_addc_u32 s101, s93, 0
	v_bfe_u32 v131, v202, 4, 2
	v_lshlrev_b32_e32 v131, 2, v131
	v_mad_i64_i32 v[4:5], s[0:1], v36, s96, v[4:5]
	v_lshlrev_b32_e32 v0, 5, v3
	v_lshl_add_u64 v[4:5], v[4:5], 0, v[0:1]
	v_lshlrev_b32_e32 v0, 11, v35
	v_cmp_eq_u32_e64 s[40:41], 0, v35
	v_lshl_add_u64 v[6:7], v[4:5], 0, v[0:1]
	v_mov_b32_e32 v51, v1
	v_cndmask_b32_e64 v0, v216, v217, s[40:41]
	v_lshlrev_b32_e32 v50, 1, v0
	v_lshl_add_u64 v[4:5], v[4:5], 0, v[50:51]
	global_load_dwordx4 v[30:33], v[6:7], off offset:16
	global_load_dwordx4 v[26:29], v[6:7], off
	global_load_dwordx4 v[22:25], v[4:5], off offset:16 nt
	global_load_dwordx4 v[18:21], v[4:5], off nt
	v_lshlrev_b32_e32 v38, 4, v3
	v_and_b32_e32 v0, 64, v2
	v_bfe_u32 v34, v2, 4, 2
	v_cmp_ne_u32_e32 vcc, 0, v0
	v_lshlrev_b32_e32 v0, 2, v38
	s_and_saveexec_b64 s[0:1], vcc
	s_xor_b64 s[0:1], exec, s[0:1]
	s_cbranch_execz .LBB0_696
	v_readlane_b32 s8, v250, 33
	v_readlane_b32 s9, v250, 34
	s_nop 4
	global_load_dwordx4 v[2:5], v0, s[8:9] offset:48
	global_load_dwordx4 v[6:9], v0, s[8:9] offset:32
	global_load_dwordx4 v[10:13], v0, s[8:9] offset:16
	global_load_dwordx4 v[14:17], v0, s[8:9]

; DI void phase_post(const Params& p, int l, int G, int bid) {
;     ...
;     for (int it = bid * 8 + wave; it < MSEG * 2; it += G * 8) {
;         const int lrow = it >> 1, grp = it & 1;
;         bf16_t* cp = P + (size_t)lrow * NPC + grp * 1024 + 16 * lane;
;         const u32x4 c0 = nc0, c1 = nc1, z0 = nz0, z1 = nz1, o0 = no0, o1 = no1;
;         const float inv = (grp == 0) ? 1.0f / ndn : 1.f;
;         if (it + G * 8 < MSEG * 2) PP_LOAD(it + G * 8);
.LBB0_701:
	v_add_u32_e32 v65, 8, v60
	s_mov_b32 s0, s38
	v_cmp_gt_i32_e32 vcc, s0, v65
	s_add_i32 s0, s38, -1
	v_cmp_lt_i32_e64 s[0:1], s0, v65
	s_or_b64 s[44:45], s[0:1], s[44:45]
	s_and_saveexec_b64 s[0:1], vcc
	s_cbranch_execz .LBB0_700
	v_ashrrev_i32_e32 v58, 1, v65
	v_mad_i64_i32 v[42:43], s[8:9], v58, s96, v[52:53]
	v_mov_b32_e32 v51, v1
	v_lshl_add_u64 v[38:39], v[42:43], 0, v[0:1]
	v_lshl_add_u64 v[46:47], v[42:43], 0, v[50:51]
	global_load_dwordx4 v[34:37], v[38:39], off offset:16
	s_nop 0
	global_load_dwordx4 v[38:41], v[38:39], off
	s_nop 0
	global_load_dwordx4 v[42:45], v[46:47], off offset:16 nt
	s_nop 0
	global_load_dwordx4 v[46:49], v[46:47], off nt
	v_mov_b32_e32 v51, v66
	s_and_saveexec_b64 s[46:47], s[40:41]
	s_cbranch_execz .LBB0_699
	v_lshl_add_u32 v130, v58, 4, v131
	v_lshlrev_b32_e32 v129, 3, v130
	global_load_dwordx4 v[120:123], v129, s[98:99]
	global_load_dwordx4 v[124:127], v129, s[98:99] offset:16
	global_load_dword v128, v130, s[100:101]
	s_branch .LBB0_699
